# v6 + nt on init-phase x row loads and final f32 output stores
# baseline (speedup 1.0000x reference)
.LBB0_197:
	s_or_b64 exec, exec, s[36:37]
	v_mov_b32_e32 v1, v0
	s_waitcnt lgkmcnt(0)
	s_barrier
	v_mov_b32_e32 v34, 0
	v_readfirstlane_b32 s0, v1
	s_ashr_i32 s4, s0, 6
	s_add_i32 s37, s4, s12
	s_cmpk_lt_i32 s37, 0x4200
	v_and_b32_e32 v2, 63, v1
	s_cselect_b64 s[2:3], -1, 0
	s_and_b64 vcc, exec, s[2:3]
	v_lshlrev_b32_e32 v66, 5, v2
	v_mov_b32_e32 v35, 0
	v_mov_b32_e32 v36, 0
	v_mov_b32_e32 v37, 0
	v_mov_b32_e32 v38, 0
	v_mov_b32_e32 v39, v34
	v_mov_b32_e32 v40, 0
	v_mov_b32_e32 v41, v34
	v_mov_b32_e32 v42, 0
	v_mov_b32_e32 v43, 0
	v_mov_b32_e32 v44, 0
	v_mov_b32_e32 v45, 0
	v_mov_b32_e32 v46, 0
	v_mov_b32_e32 v47, v34
	v_mov_b32_e32 v48, 0
	v_mov_b32_e32 v49, v34
	v_mov_b32_e32 v50, 0
	v_mov_b32_e32 v51, 0
	v_mov_b32_e32 v52, 0
	v_mov_b32_e32 v53, 0
	v_mov_b32_e32 v54, 0
	v_mov_b32_e32 v55, v34
	v_mov_b32_e32 v56, 0
	v_mov_b32_e32 v57, v34
	v_mov_b32_e32 v62, 0
	v_mov_b32_e32 v63, 0
	v_mov_b32_e32 v64, 0
	v_mov_b32_e32 v65, 0
	v_mov_b32_e32 v58, 0
	v_mov_b32_e32 v59, 0
	v_mov_b32_e32 v60, 0
	v_mov_b32_e32 v61, v34
	s_cbranch_vccz .LBB0_199
	s_add_i32 s0, s37, 0xffffc000
	s_ashr_i32 s1, s37, 31
	s_cmpk_lt_i32 s37, 0x4000
	s_cselect_b32 s1, s1, 0
	s_cselect_b32 s0, s37, s0
	s_cselect_b32 s5, s41, s45
	s_cselect_b32 s6, s40, s44
	s_lshl_b64 s[0:1], s[0:1], 13
	s_add_u32 s0, s6, s0
	s_addc_u32 s1, s5, s1
	v_mov_b32_e32 v67, 0
	v_lshl_add_u64 v[4:5], s[0:1], 0, v[66:67]
	global_load_dwordx4 v[34:37], v66, s[0:1] nt
	global_load_dwordx4 v[38:41], v66, s[0:1] offset:16 nt
	global_load_dwordx4 v[42:45], v66, s[0:1] offset:2048 nt
	global_load_dwordx4 v[46:49], v66, s[0:1] offset:2064 nt
	s_mov_b64 s[0:1], 0x1000
	v_lshl_add_u64 v[6:7], v[4:5], 0, s[0:1]
	s_movk_i32 s0, 0x1000
	v_add_co_u32_e32 v8, vcc, s0, v4
	s_mov_b64 s[0:1], 0x1800
	s_nop 0
	v_addc_co_u32_e32 v9, vcc, 0, v5, vcc
	global_load_dwordx4 v[50:53], v[8:9], off nt
	global_load_dwordx4 v[54:57], v[6:7], off offset:16 nt
	v_lshl_add_u64 v[4:5], v[4:5], 0, s[0:1]
	global_load_dwordx4 v[62:65], v[8:9], off offset:2048 nt
	global_load_dwordx4 v[58:61], v[4:5], off offset:16 nt

.LBB0_203:
	s_add_i32 s36, s37, s94
	s_cmpk_gt_i32 s36, 0x41ff
	s_cselect_b64 s[18:19], -1, 0
	s_cmpk_lt_i32 s36, 0x4200
	s_cselect_b32 s0, s36, s37
	s_add_i32 s2, s0, 0xffffc000
	s_ashr_i32 s1, s0, 31
	s_cmpk_lt_i32 s0, 0x4000
	s_cselect_b32 s1, s1, 0
	s_cselect_b32 s0, s0, s2
	s_cselect_b32 s2, s41, s45
	s_cselect_b32 s3, s40, s44
	s_lshl_b64 s[0:1], s[0:1], 13
	s_add_u32 s0, s3, s0
	s_addc_u32 s1, s2, s1
	v_lshlrev_b32_e32 v66, 4, v68
	v_lshl_add_u64 v[2:3], s[0:1], 0, v[66:67]
	global_load_dwordx4 v[26:29], v66, s[0:1] offset:16 nt
	global_load_dwordx4 v[30:33], v66, s[0:1] nt
	global_load_dwordx4 v[6:9], v66, s[0:1] offset:2064 nt
	global_load_dwordx4 v[18:21], v66, s[0:1] offset:2048 nt
	v_add_co_u32_e32 v10, vcc, 0x1000, v2
	v_lshl_add_u64 v[4:5], v[2:3], 0, s[10:11]
	s_nop 0
	v_addc_co_u32_e32 v11, vcc, 0, v3, vcc
	v_lshl_add_u64 v[2:3], v[2:3], 0, s[14:15]
	global_load_dwordx4 v[22:25], v[10:11], off nt
	global_load_dwordx4 v[14:17], v[4:5], off offset:16 nt
	s_nop 0
	global_load_dwordx4 v[10:13], v[10:11], off offset:2048 nt
	s_nop 0
	global_load_dwordx4 v[2:5], v[2:3], off offset:16 nt
	s_cmpk_lt_i32 s37, 0x4000
	s_mov_b64 s[2:3], -1
	s_cbranch_scc1 .LBB0_205
	s_mov_b64 s[2:3], 0

.LBB0_1794:
	s_waitcnt vmcnt(0)
	v_cvt_f32_f16_sdwa v79, v62 dst_sel:DWORD dst_unused:UNUSED_PAD src0_sel:WORD_1
	v_cvt_f32_f16_e32 v78, v62
	v_cvt_f32_f16_sdwa v81, v63 dst_sel:DWORD dst_unused:UNUSED_PAD src0_sel:WORD_1
	v_cvt_f32_f16_e32 v80, v63
	v_cvt_f32_f16_sdwa v63, v64 dst_sel:DWORD dst_unused:UNUSED_PAD src0_sel:WORD_1
	v_cvt_f32_f16_e32 v62, v64
	v_pk_mul_f32 v[84:85], v[78:79], v[78:79]
	v_pk_mul_f32 v[86:87], v[80:81], v[80:81]
	v_cvt_f32_f16_sdwa v91, v65 dst_sel:DWORD dst_unused:UNUSED_PAD src0_sel:WORD_1
	v_cvt_f32_f16_e32 v90, v65
	v_add_f32_e32 v84, v84, v85
	v_add_f32_e32 v84, v86, v84
	v_pk_mul_f32 v[88:89], v[62:63], v[62:63]
	v_cvt_f32_f16_sdwa v65, v58 dst_sel:DWORD dst_unused:UNUSED_PAD src0_sel:WORD_1
	v_cvt_f32_f16_e32 v64, v58
	v_add_f32_e32 v84, v87, v84
	v_add_f32_e32 v84, v88, v84
	v_cvt_f32_f16_sdwa v93, v59 dst_sel:DWORD dst_unused:UNUSED_PAD src0_sel:WORD_1
	v_cvt_f32_f16_e32 v92, v59
	v_pk_mul_f32 v[94:95], v[90:91], v[90:91]
	v_add_f32_e32 v84, v89, v84
	v_add_f32_e32 v84, v94, v84
	v_cvt_f32_f16_sdwa v59, v60 dst_sel:DWORD dst_unused:UNUSED_PAD src0_sel:WORD_1
	v_cvt_f32_f16_e32 v58, v60
	v_pk_mul_f32 v[96:97], v[64:65], v[64:65]
	v_add_f32_e32 v84, v95, v84
	v_add_f32_e32 v84, v96, v84
	v_pk_mul_f32 v[98:99], v[92:93], v[92:93]
	v_cvt_f32_f16_sdwa v103, v61 dst_sel:DWORD dst_unused:UNUSED_PAD src0_sel:WORD_1
	v_cvt_f32_f16_e32 v102, v61
	v_add_f32_e32 v84, v97, v84
	v_add_f32_e32 v84, v98, v84
	v_pk_mul_f32 v[100:101], v[58:59], v[58:59]
	v_cvt_f32_f16_sdwa v61, v54 dst_sel:DWORD dst_unused:UNUSED_PAD src0_sel:WORD_1
	v_cvt_f32_f16_e32 v60, v54
	v_add_f32_e32 v84, v99, v84
	v_add_f32_e32 v84, v100, v84
	v_cvt_f32_f16_sdwa v105, v55 dst_sel:DWORD dst_unused:UNUSED_PAD src0_sel:WORD_1
	v_cvt_f32_f16_e32 v104, v55
	v_pk_mul_f32 v[106:107], v[102:103], v[102:103]
	v_add_f32_e32 v84, v101, v84
	v_add_f32_e32 v84, v106, v84
	v_cvt_f32_f16_sdwa v55, v56 dst_sel:DWORD dst_unused:UNUSED_PAD src0_sel:WORD_1
	v_cvt_f32_f16_e32 v54, v56
	v_pk_mul_f32 v[108:109], v[60:61], v[60:61]
	v_add_f32_e32 v84, v107, v84
	v_add_f32_e32 v84, v108, v84
	v_pk_mul_f32 v[110:111], v[104:105], v[104:105]
	v_cvt_f32_f16_sdwa v115, v57 dst_sel:DWORD dst_unused:UNUSED_PAD src0_sel:WORD_1
	v_cvt_f32_f16_e32 v114, v57
	v_add_f32_e32 v84, v109, v84
	v_add_f32_e32 v84, v110, v84
	v_pk_mul_f32 v[112:113], v[54:55], v[54:55]
	v_cvt_f32_f16_sdwa v57, v50 dst_sel:DWORD dst_unused:UNUSED_PAD src0_sel:WORD_1
	v_cvt_f32_f16_e32 v56, v50
	v_add_f32_e32 v84, v111, v84
	v_add_f32_e32 v84, v112, v84
	v_cvt_f32_f16_sdwa v117, v51 dst_sel:DWORD dst_unused:UNUSED_PAD src0_sel:WORD_1
	v_cvt_f32_f16_e32 v116, v51
	v_pk_mul_f32 v[50:51], v[114:115], v[114:115]
	v_add_f32_e32 v84, v113, v84
	v_add_f32_e32 v50, v50, v84
	v_cvt_f32_f16_sdwa v77, v53 dst_sel:DWORD dst_unused:UNUSED_PAD src0_sel:WORD_1
	v_cvt_f32_f16_e32 v76, v53
	v_cvt_f32_f16_sdwa v119, v52 dst_sel:DWORD dst_unused:UNUSED_PAD src0_sel:WORD_1
	v_cvt_f32_f16_e32 v118, v52
	v_pk_mul_f32 v[52:53], v[56:57], v[56:57]
	v_add_f32_e32 v50, v51, v50
	v_add_f32_e32 v50, v52, v50
	v_pk_mul_f32 v[120:121], v[116:117], v[116:117]
	v_add_f32_e32 v50, v53, v50
	v_add_f32_e32 v50, v120, v50
	v_pk_mul_f32 v[122:123], v[118:119], v[118:119]
	v_add_f32_e32 v50, v121, v50
	v_add_f32_e32 v50, v122, v50
	v_pk_mul_f32 v[82:83], v[76:77], v[76:77]
	v_add_f32_e32 v50, v123, v50
	v_add_f32_e32 v50, v82, v50
	v_add_f32_e32 v50, v83, v50
	ds_bpermute_b32 v51, v70, v50
	s_mov_b32 s0, 0xf800000
	s_waitcnt lgkmcnt(0)
	v_add_f32_e32 v50, v50, v51
	ds_bpermute_b32 v51, v71, v50
	s_waitcnt lgkmcnt(0)
	v_add_f32_e32 v50, v50, v51
	ds_bpermute_b32 v51, v72, v50
	s_waitcnt lgkmcnt(0)
	v_add_f32_e32 v50, v50, v51
	ds_bpermute_b32 v51, v73, v50
	s_waitcnt lgkmcnt(0)
	v_add_f32_e32 v50, v50, v51
	ds_bpermute_b32 v51, v74, v50
	s_waitcnt lgkmcnt(0)
	v_add_f32_e32 v50, v50, v51
	ds_bpermute_b32 v51, v75, v50
	s_waitcnt lgkmcnt(0)
	v_add_f32_e32 v50, v50, v51
	v_mov_b32_e32 v51, 0x358637bd
	v_fmamk_f32 v50, v50, 0x3a000000, v51
	v_mul_f32_e32 v51, 0x4f800000, v50
	v_cmp_gt_f32_e32 vcc, s0, v50
	s_nop 1
	v_cndmask_b32_e32 v50, v50, v51, vcc
	v_sqrt_f32_e32 v51, v50
	s_nop 0
	v_add_u32_e32 v52, -1, v51
	v_fma_f32 v53, -v52, v51, v50
	v_cmp_ge_f32_e64 s[2:3], 0, v53
	v_add_u32_e32 v53, 1, v51
	s_nop 0
	v_cndmask_b32_e64 v52, v51, v52, s[2:3]
	v_fma_f32 v51, -v53, v51, v50
	v_cmp_lt_f32_e64 s[2:3], 0, v51
	s_nop 1
	v_cndmask_b32_e64 v51, v52, v53, s[2:3]
	v_mul_f32_e32 v52, 0x37800000, v51
	v_cndmask_b32_e32 v51, v51, v52, vcc
	v_cmp_class_f32_e32 vcc, v50, v0
	s_nop 1
	v_cndmask_b32_e32 v50, v51, v50, vcc
	v_div_scale_f32 v51, s[0:1], v50, v50, 1.0
	v_rcp_f32_e32 v52, v51
	v_readlane_b32 s0, v254, 60
	v_readlane_b32 s1, v254, 61
	v_fma_f32 v53, -v51, v52, 1.0
	v_fmac_f32_e32 v52, v53, v52
	v_div_scale_f32 v53, vcc, 1.0, v50, 1.0
	v_mul_f32_e32 v82, v53, v52
	v_fma_f32 v83, -v51, v82, v53
	v_fmac_f32_e32 v82, v83, v52
	v_fma_f32 v51, -v51, v82, v53
	v_div_fmas_f32 v51, v51, v52, v82
	v_div_fixup_f32 v82, v51, v50, 1.0
	v_pk_mul_f32 v[50:51], v[82:83], v[78:79] op_sel_hi:[0,1]
	v_pk_mul_f32 v[52:53], v[82:83], v[80:81] op_sel_hi:[0,1]
	v_pk_mul_f32 v[52:53], v[8:9], v[52:53]
	v_pk_mul_f32 v[50:51], v[6:7], v[50:51]
	global_store_dwordx4 v[66:67], v[50:53], off offset:-4096 nt
	s_andn2_b64 vcc, exec, s[6:7]
	s_nop 0
	v_pk_mul_f32 v[50:51], v[82:83], v[62:63] op_sel_hi:[0,1]
	v_pk_mul_f32 v[52:53], v[82:83], v[90:91] op_sel_hi:[0,1]
	v_pk_mul_f32 v[52:53], v[4:5], v[52:53]
	v_pk_mul_f32 v[50:51], v[2:3], v[50:51]
	global_store_dwordx4 v[66:67], v[50:53], off offset:-4080 nt
	v_mov_b32_e32 v62, v34
	v_mov_b32_e32 v63, v35
	v_pk_mul_f32 v[50:51], v[82:83], v[64:65] op_sel_hi:[0,1]
	v_pk_mul_f32 v[52:53], v[82:83], v[92:93] op_sel_hi:[0,1]
	v_pk_mul_f32 v[52:53], v[16:17], v[52:53]
	v_pk_mul_f32 v[50:51], v[14:15], v[50:51]
	global_store_dwordx4 v[66:67], v[50:53], off offset:-2048 nt
	v_mov_b32_e32 v64, v36
	v_mov_b32_e32 v65, v37
	v_pk_mul_f32 v[50:51], v[82:83], v[58:59] op_sel_hi:[0,1]
	v_pk_mul_f32 v[52:53], v[82:83], v[102:103] op_sel_hi:[0,1]
	v_pk_mul_f32 v[52:53], v[12:13], v[52:53]
	v_pk_mul_f32 v[50:51], v[10:11], v[50:51]
	global_store_dwordx4 v[66:67], v[50:53], off offset:-2032 nt
	v_mov_b32_e32 v58, v38
	v_mov_b32_e32 v59, v39
	v_pk_mul_f32 v[50:51], v[82:83], v[60:61] op_sel_hi:[0,1]
	v_pk_mul_f32 v[52:53], v[82:83], v[104:105] op_sel_hi:[0,1]
	v_pk_mul_f32 v[52:53], v[20:21], v[52:53]
	v_pk_mul_f32 v[50:51], v[18:19], v[50:51]
	global_store_dwordx4 v[66:67], v[50:53], off nt
	v_mov_b32_e32 v60, v40
	v_mov_b32_e32 v61, v41
	v_pk_mul_f32 v[50:51], v[82:83], v[54:55] op_sel_hi:[0,1]
	v_pk_mul_f32 v[52:53], v[82:83], v[114:115] op_sel_hi:[0,1]
	v_pk_mul_f32 v[52:53], v[24:25], v[52:53]
	v_pk_mul_f32 v[50:51], v[22:23], v[50:51]
	global_store_dwordx4 v[66:67], v[50:53], off offset:16 nt
	v_mov_b32_e32 v54, v42
	v_mov_b32_e32 v55, v43
	v_pk_mul_f32 v[50:51], v[82:83], v[56:57] op_sel_hi:[0,1]
	v_pk_mul_f32 v[52:53], v[82:83], v[116:117] op_sel_hi:[0,1]
	v_pk_mul_f32 v[52:53], v[28:29], v[52:53]
	v_pk_mul_f32 v[50:51], v[26:27], v[50:51]
	global_store_dwordx4 v[66:67], v[50:53], off offset:2048 nt
	v_mov_b32_e32 v56, v44
	v_mov_b32_e32 v57, v45
	v_pk_mul_f32 v[50:51], v[82:83], v[118:119] op_sel_hi:[0,1]
	v_pk_mul_f32 v[52:53], v[82:83], v[76:77] op_sel_hi:[0,1]
	v_pk_mul_f32 v[52:53], v[32:33], v[52:53]
	v_pk_mul_f32 v[50:51], v[30:31], v[50:51]
	global_store_dwordx4 v[66:67], v[50:53], off offset:2064 nt
	v_lshl_add_u64 v[66:67], v[66:67], 0, s[0:1]
	v_readlane_b32 s0, v254, 62
	v_readlane_b32 s1, v254, 63
	v_mov_b32_e32 v50, v46
	v_mov_b32_e32 v51, v47
	v_lshl_add_u64 v[68:69], v[68:69], 0, s[0:1]
	v_mov_b32_e32 v52, v48
	v_mov_b32_e32 v53, v49
	s_cbranch_vccz .LBB0_1797
